# early acquire also in the F/G a_ready waits and the conv / pool in-loop claim waits
# baseline (speedup 1.0000x reference)
.LBB0_791:
	s_or_b64 exec, exec, s[22:23]
	s_waitcnt vmcnt(0)
	s_nop 0
	s_waitcnt vmcnt(0)

.LBB0_923:
	s_or_b64 exec, exec, s[0:1]
	v_and_b32_e32 v50, 0xffff0000, v51
	v_fma_f32 v51, v92, v50, v74
	v_mul_f32_e32 v50, 0xbfb8aa3b, v108
	v_exp_f32_e32 v50, v50
	v_ashrrev_i32_e32 v111, 31, v110
	v_add_f32_e32 v50, 1.0, v50
	v_rcp_f32_e32 v52, v50
	v_mul_f32_e32 v50, 0xbfb8aa3b, v109
	v_exp_f32_e32 v50, v50
	s_nop 0
	v_add_f32_e32 v50, 1.0, v50
	v_rcp_f32_e32 v53, v50
	v_mul_f32_e32 v50, 0xbfb8aa3b, v80
	v_exp_f32_e32 v50, v50
	v_pk_mul_f32 v[52:53], v[108:109], v[52:53]
	v_add_f32_e32 v50, 1.0, v50
	v_rcp_f32_e32 v54, v50
	v_mul_f32_e32 v50, 0xbfb8aa3b, v81
	v_exp_f32_e32 v50, v50
	s_nop 0
	v_add_f32_e32 v50, 1.0, v50
	v_rcp_f32_e32 v55, v50
	v_mul_f32_e32 v50, 0xbfb8aa3b, v48
	v_exp_f32_e32 v50, v50
	v_pk_mul_f32 v[54:55], v[80:81], v[54:55]
	v_add_f32_e32 v50, 1.0, v50
	v_rcp_f32_e32 v56, v50
	v_mul_f32_e32 v50, 0xbfb8aa3b, v49
	v_exp_f32_e32 v50, v50
	s_nop 0
	v_add_f32_e32 v50, 1.0, v50
	v_rcp_f32_e32 v57, v50
	v_mov_b32_e32 v50, v75
	v_pk_mul_f32 v[56:57], v[48:49], v[56:57]
	v_mul_f32_e32 v48, 0xbfb8aa3b, v75
	v_mul_f32_e32 v49, 0xbfb8aa3b, v51
	v_exp_f32_e32 v48, v48
	v_exp_f32_e32 v49, v49
	v_add_f32_e32 v48, 1.0, v48
	v_add_f32_e32 v49, 1.0, v49
	v_rcp_f32_e32 v48, v48
	v_rcp_f32_e32 v49, v49
	s_nop 0
	v_pk_mul_f32 v[58:59], v[50:51], v[48:49]
	v_cvt_pk_bf16_f32 v48, v52, v53
	v_lshlrev_b64 v[52:53], 13, v[110:111]
	v_cvt_pk_bf16_f32 v49, v54, v55
	v_cvt_pk_bf16_f32 v50, v56, v57
	v_cvt_pk_bf16_f32 v51, v58, v59
	v_lshl_add_u64 v[52:53], v[88:89], 0, v[52:53]
	global_store_dwordx4 v[52:53], v[48:51], off
	s_and_saveexec_b64 s[0:1], s[2:3]
	s_xor_b64 s[0:1], exec, s[0:1]
	v_xor_b32_e32 v168, 1, v168
	s_andn2_saveexec_b64 s[0:1], s[0:1]
	s_cbranch_execz .LBB0_793
	s_movk_i32 s6, 0x220
	v_cmp_gt_u32_e32 vcc, s6, v106
	v_mov_b32_e32 v52, 0xffff
	s_and_saveexec_b64 s[20:21], vcc
	s_cbranch_execz .LBB0_792
	v_mov_b32_e32 v107, v65
	s_getpc_b64 s[6:7]
	s_add_u32 s6, s6, _ZL9CONV_PERM@rel32@lo+4
	s_addc_u32 s7, s7, _ZL9CONV_PERM@rel32@hi+12
	v_lshl_add_u64 v[48:49], v[106:107], 1, s[6:7]
	global_load_ushort v52, v[48:49], off
	s_mov_b64 s[22:23], 0
	s_waitcnt vmcnt(0)
	v_lshlrev_b32_e32 v48, 5, v52
	v_sub_u32_e64 v49, v48, 2 clamp
	v_min_u32_e32 v48, 0x43de, v48
	v_add_u32_e32 v51, 33, v48
	v_and_b32_e32 v64, 0x1fff00, v49
	v_lshrrev_b32_e32 v50, 8, v49
	v_lshrrev_b32_e32 v53, 8, v51
	v_lshl_add_u64 v[48:49], s[12:13], 0, v[64:65]
	v_and_b32_e32 v64, 0xff00, v51
	v_cmp_ne_u32_e64 s[6:7], v53, v50
	v_lshl_add_u64 v[50:51], s[12:13], 0, v[64:65]
	v_mov_b32_e32 v53, 0
	buffer_inv sc1
	s_branch .LBB0_933

.LBB0_1364:
	s_or_b64 exec, exec, s[8:9]
	s_waitcnt vmcnt(0)
	s_nop 0
	s_waitcnt vmcnt(0)

.LBB0_1503:
	s_or_b64 exec, exec, s[0:1]
	v_add_u32_e32 v0, v67, v0
	v_min_i32_e32 v0, v0, v3
	v_sub_u32_e32 v0, v0, v1
	v_add_u32_e32 v0, v0, v66
	v_cvt_f32_i32_e32 v0, v0
	v_lshlrev_b32_e32 v64, 1, v2
	v_ashrrev_i32_e32 v81, 31, v80
	v_lshl_add_u64 v[4:5], v[4:5], 0, v[64:65]
	v_rcp_iflag_f32_e32 v0, v0
	s_nop 0
	v_pk_fma_f32 v[0:1], v[62:63], v[0:1], v[6:7] op_sel_hi:[1,0,1] neg_lo:[0,0,1] neg_hi:[0,0,1]
	s_nop 0
	v_cvt_pk_bf16_f32 v2, v0, v1
	v_lshlrev_b64 v[0:1], 11, v[80:81]
	v_lshl_add_u64 v[0:1], v[4:5], 0, v[0:1]
	global_store_dword v[0:1], v2, off
	s_and_saveexec_b64 s[0:1], s[2:3]
	s_xor_b64 s[0:1], exec, s[0:1]
	v_xor_b32_e32 v111, 1, v111
	s_andn2_saveexec_b64 s[0:1], s[0:1]
	s_cbranch_execz .LBB0_1366
	v_lshlrev_b32_e32 v0, 1, v112
	v_cmp_gt_i32_e32 vcc, s36, v0
	s_and_saveexec_b64 s[6:7], vcc
	s_cbranch_execz .LBB0_1365
	v_add_u32_e32 v0, 0xfffffc00, v0
	v_lshrrev_b32_e32 v0, 4, v0
	s_movk_i32 s8, 0x200
	v_lshrrev_b32_e32 v1, 3, v112
	v_add_u32_e32 v0, 64, v0
	v_cmp_gt_i32_e32 vcc, s8, v112
	s_nop 1
	v_cndmask_b32_e32 v0, v0, v1, vcc
	v_lshlrev_b32_e32 v0, 6, v0
	v_ashrrev_i32_e32 v1, 31, v0
	v_lshl_add_u64 v[0:1], v[0:1], 2, s[16:17]
	buffer_inv sc1
	global_load_dword v2, v[0:1], off sc1
	s_waitcnt vmcnt(0)
	v_cmp_gt_u32_e32 vcc, 32, v2
	s_and_saveexec_b64 s[8:9], vcc
	s_cbranch_execz .LBB0_1364
	s_mov_b32 s39, 1
	s_mov_b64 s[10:11], 0
	s_branch .LBB0_1510

.LBB0_1663:
	s_and_b64 vcc, exec, s[6:7]
	v_readlane_b32 s6, v255, 8
	s_add_i32 s47, s6, 0x6200
	v_readlane_b32 s7, v255, 9
	s_cbranch_vccnz .LBB0_1720
	s_getreg_b32 s6, hwreg(HW_REG_HW_ID, 0, 6)
	s_and_b32 s6, s6, 63
	s_lshl_b32 s6, s6, 2
	s_add_i32 s6, s6, 0
	s_add_i32 s6, s6, 0x27400
	v_mov_b32_e32 v0, s6
	ds_read_b32 v0, v0
	s_waitcnt lgkmcnt(0)
	v_readfirstlane_b32 s6, v0
	s_cmp_lg_u32 s6, 0
	s_cbranch_scc1 .LBB0_1680
	s_lshl_b32 s6, s8, 6
	s_add_i32 s6, s6, s51
	s_ashr_i32 s7, s6, 31
	s_lshl_b64 s[6:7], s[6:7], 2
	s_add_u32 s12, s0, s6
	s_addc_u32 s13, s1, s7
	s_add_u32 s6, s0, 0x4200
	s_addc_u32 s7, s1, 0
	s_mov_b32 s9, 1
	buffer_inv sc1
	s_branch .LBB0_1667

.LBB0_1679:
	s_waitcnt vmcnt(0)
	s_nop 0
	s_waitcnt vmcnt(0)

.LBB0_1725:
	s_and_b64 vcc, exec, s[6:7]
	s_cbranch_vccnz .LBB0_1782
	s_getreg_b32 s6, hwreg(HW_REG_HW_ID, 0, 6)
	s_and_b32 s6, s6, 63
	s_lshl_b32 s6, s6, 2
	s_add_i32 s6, s6, 0
	s_add_i32 s6, s6, 0x27400
	v_mov_b32_e32 v0, s6
	ds_read_b32 v0, v0
	s_waitcnt lgkmcnt(0)
	v_readfirstlane_b32 s6, v0
	s_cmp_lg_u32 s6, 0
	s_cbranch_scc1 .LBB0_1742
	s_lshl_b32 s6, s12, 6
	s_add_i32 s6, s6, s47
	s_ashr_i32 s7, s6, 31
	s_lshl_b64 s[6:7], s[6:7], 2
	s_add_u32 s14, s8, s6
	s_addc_u32 s15, s9, s7
	s_add_u32 s6, s8, 0x4200
	s_addc_u32 s7, s9, 0
	s_mov_b32 s13, 1
	buffer_inv sc1
	s_branch .LBB0_1729

.LBB0_1788:
	s_and_b64 vcc, exec, s[6:7]
	s_cbranch_vccnz .LBB0_1845
	s_getreg_b32 s1, hwreg(HW_REG_HW_ID, 0, 6)
	s_and_b32 s1, s1, 63
	s_lshl_b32 s1, s1, 2
	s_add_i32 s1, s1, 0
	s_add_i32 s1, s1, 0x27400
	v_mov_b32_e32 v0, s1
	ds_read_b32 v0, v0
	s_waitcnt lgkmcnt(0)
	v_readfirstlane_b32 s1, v0
	s_cmp_lg_u32 s1, 0
	s_cbranch_scc1 .LBB0_1805
	s_lshl_b32 s1, s0, 6
	s_add_i32 s6, s1, s47
	s_ashr_i32 s7, s6, 31
	s_lshl_b64 s[6:7], s[6:7], 2
	s_add_u32 s12, s8, s6
	s_addc_u32 s13, s9, s7
	s_add_u32 s6, s8, 0x4200
	s_addc_u32 s7, s9, 0
	s_mov_b32 s1, 1
	buffer_inv sc1
	s_branch .LBB0_1792
